# norm0 token loop: all 16 loads of a token (x row and 12 modulation quarters) issued up front with private registers and counted waits
# speedup vs baseline: 1.0041x; 1.0041x over previous
.LBB0_194:
	s_or_b64 exec, exec, s[0:1]
	v_lshl_add_u64 v[52:53], v[0:1], 0, v[12:13]
	v_lshrrev_b32_e32 v0, 12, v6
	s_movk_i32 s0, 0x1800
	v_mad_u32_u24 v0, v0, s0, s0
	v_cndmask_b32_e64 v6, v0, 0, vcc
	v_lshl_add_u64 v[0:1], v[6:7], 2, s[88:89]
	s_mov_b64 s[0:1], 0x1000
	v_lshl_add_u64 v[54:55], v[0:1], 0, s[0:1]
	v_lshlrev_b64 v[2:3], 11, v[4:5]
	v_lshl_add_u64 v[24:25], v[54:55], 0, v[12:13]
	v_lshl_add_u64 v[22:23], v[0:1], 0, v[12:13]
	v_lshl_add_u64 v[20:21], v[10:11], 0, v[2:3]
	global_load_dwordx4 v[36:39], v[52:53], off
	global_load_dwordx4 v[40:43], v[8:9], off
	s_nop 0
	global_load_dwordx4 v[24:27], v[24:25], off
	s_nop 0
	global_load_dwordx4 v[0:3], v[22:23], off
	global_load_dwordx4 v[44:47], v[52:53], off offset:1024
	v_lshl_add_u64 v[104:105], v[54:55], 0, v[14:15]
	v_lshl_add_u64 v[106:107], v[54:55], 0, v[16:17]
	v_lshl_add_u64 v[62:63], v[54:55], 0, v[18:19]
	global_load_dwordx4 v[88:91], v[52:53], off offset:2048
	global_load_dwordx4 v[92:95], v[52:53], off offset:3072
	global_load_dwordx4 v[96:99], v[8:9], off offset:1024
	global_load_dwordx4 v[100:103], v[104:105], off
	global_load_dwordx4 v[108:111], v[22:23], off offset:1024
	global_load_dwordx4 v[112:115], v[8:9], off offset:2048
	global_load_dwordx4 v[116:119], v[106:107], off
	global_load_dwordx4 v[120:123], v[22:23], off offset:2048
	global_load_dwordx4 v[124:127], v[8:9], off offset:3072
	global_load_dwordx4 v[128:131], v[62:63], off
	global_load_dwordx4 v[132:135], v[22:23], off offset:3072
	s_mov_b32 s0, 0x800000
	v_add_u32_e32 v4, s8, v4
	s_waitcnt vmcnt(15)
	v_mov_b32_e32 v48, v37
	s_waitcnt vmcnt(13)
	v_pk_add_f32 v[56:57], v[26:27], 1.0 op_sel_hi:[1,0]
	v_mov_b32_e32 v26, v36
	s_waitcnt vmcnt(11)
	v_mov_b32_e32 v49, v45
	v_mov_b32_e32 v27, v44
	v_pk_mul_f32 v[48:49], v[48:49], v[48:49]
	v_pk_add_f32 v[58:59], v[24:25], 1.0 op_sel_hi:[1,0]
	v_pk_fma_f32 v[26:27], v[26:27], v[26:27], v[48:49]
	v_mov_b32_e32 v48, v38
	v_mov_b32_e32 v49, v46
	v_pk_fma_f32 v[26:27], v[48:49], v[48:49], v[26:27]
	v_mov_b32_e32 v48, v39
	v_mov_b32_e32 v49, v47
	v_pk_fma_f32 v[60:61], v[48:49], v[48:49], v[26:27]
	v_add_f32_e32 v5, v60, v61
	s_waitcnt vmcnt(10)
	v_mov_b32_e32 v66, v89
	v_mov_b32_e32 v64, v88
	s_waitcnt vmcnt(9)
	v_mov_b32_e32 v67, v93
	v_mov_b32_e32 v65, v92
	v_pk_mul_f32 v[66:67], v[66:67], v[66:67]
	s_nop 0
	v_pk_fma_f32 v[64:65], v[64:65], v[64:65], v[66:67]
	v_mov_b32_e32 v66, v90
	v_mov_b32_e32 v67, v94
	v_pk_fma_f32 v[64:65], v[66:67], v[66:67], v[64:65]
	v_mov_b32_e32 v66, v91
	v_mov_b32_e32 v67, v95
	v_pk_fma_f32 v[64:65], v[66:67], v[66:67], v[64:65]
	s_nop 0
	v_add_f32_e32 v5, v5, v64
	v_add_f32_e32 v5, v5, v65
	ds_bpermute_b32 v6, v29, v5
	s_waitcnt lgkmcnt(0)
	v_add_f32_e32 v5, v5, v6
	ds_bpermute_b32 v6, v30, v5
	s_waitcnt lgkmcnt(0)
	v_add_f32_e32 v5, v5, v6
	ds_bpermute_b32 v6, v31, v5
	s_waitcnt lgkmcnt(0)
	v_add_f32_e32 v5, v5, v6
	ds_bpermute_b32 v6, v32, v5
	s_waitcnt lgkmcnt(0)
	v_add_f32_e32 v5, v5, v6
	ds_bpermute_b32 v6, v33, v5
	s_waitcnt lgkmcnt(0)
	v_add_f32_e32 v5, v5, v6
	ds_bpermute_b32 v6, v34, v5
	s_waitcnt lgkmcnt(0)
	v_add_f32_e32 v5, v5, v6
	v_fmamk_f32 v5, v5, 0x3a800000, v35
	v_cmp_gt_f32_e32 vcc, s0, v5
	v_mul_f32_e32 v6, 0x4b800000, v5
	s_movk_i32 s0, 0x2fff
	v_cndmask_b32_e32 v5, v5, v6, vcc
	v_rsq_f32_e32 v5, v5
	s_nop 0
	v_mul_f32_e32 v6, 0x45800000, v5
	v_cndmask_b32_e32 v6, v5, v6, vcc
	v_pk_mul_f32 v[36:37], v[36:37], v[6:7] op_sel_hi:[1,0]
	v_pk_mul_f32 v[38:39], v[38:39], v[6:7] op_sel_hi:[1,0]
	v_pk_mul_f32 v[36:37], v[40:41], v[36:37]
	v_pk_mul_f32 v[38:39], v[42:43], v[38:39]
	v_pk_fma_f32 v[0:1], v[58:59], v[36:37], v[0:1]
	v_pk_fma_f32 v[2:3], v[56:57], v[38:39], v[2:3]
	v_bfe_u32 v37, v1, 16, 1
	v_bfe_u32 v5, v3, 16, 1
	v_bfe_u32 v36, v2, 16, 1
	v_bfe_u32 v38, v0, 16, 1
	v_add3_u32 v0, v0, v38, s9
	v_add3_u32 v37, v1, v37, s9
	v_add3_u32 v1, v2, v36, s9
	v_add3_u32 v2, v3, v5, s9
	v_perm_b32 v1, v2, v1, s10
	v_perm_b32 v0, v37, v0, s10
	global_store_dwordx2 v[20:21], v[0:1], off
	s_nop 0
	v_pk_mul_f32 v[24:25], v[46:47], v[6:7] op_sel_hi:[1,0]
	v_pk_mul_f32 v[44:45], v[44:45], v[6:7] op_sel_hi:[1,0]
	v_cmp_lt_i32_e32 vcc, s0, v4
	s_or_b64 s[6:7], vcc, s[6:7]
	s_waitcnt vmcnt(9)
	v_pk_mul_f32 v[0:1], v[44:45], v[96:97]
	v_pk_mul_f32 v[2:3], v[24:25], v[98:99]
	s_waitcnt vmcnt(8)
	v_pk_add_f32 v[24:25], v[102:103], 1.0 op_sel_hi:[1,0]
	v_pk_add_f32 v[36:37], v[100:101], 1.0 op_sel_hi:[1,0]
	s_waitcnt vmcnt(7)
	v_pk_fma_f32 v[2:3], v[2:3], v[24:25], v[110:111]
	v_pk_fma_f32 v[0:1], v[0:1], v[36:37], v[108:109]
	v_bfe_u32 v25, v3, 16, 1
	v_bfe_u32 v5, v1, 16, 1
	v_bfe_u32 v24, v0, 16, 1
	v_bfe_u32 v36, v2, 16, 1
	v_add3_u32 v2, v2, v36, s9
	v_add3_u32 v3, v3, v25, s9
	v_add3_u32 v0, v0, v24, s9
	v_add3_u32 v1, v1, v5, s9
	v_perm_b32 v0, v1, v0, s10
	v_perm_b32 v1, v3, v2, s10
	global_store_dwordx2 v[20:21], v[0:1], off offset:512
	s_nop 0
	s_nop 0
	v_pk_mul_f32 v[40:41], v[90:91], v[6:7] op_sel_hi:[1,0]
	v_pk_mul_f32 v[42:43], v[88:89], v[6:7] op_sel_hi:[1,0]
	s_waitcnt vmcnt(7)
	v_pk_mul_f32 v[2:3], v[40:41], v[114:115]
	v_pk_mul_f32 v[0:1], v[42:43], v[112:113]
	s_waitcnt vmcnt(6)
	v_pk_add_f32 v[26:27], v[118:119], 1.0 op_sel_hi:[1,0]
	v_pk_add_f32 v[24:25], v[116:117], 1.0 op_sel_hi:[1,0]
	s_waitcnt vmcnt(5)
	v_pk_fma_f32 v[2:3], v[2:3], v[26:27], v[122:123]
	v_pk_fma_f32 v[0:1], v[0:1], v[24:25], v[120:121]
	v_bfe_u32 v25, v3, 16, 1
	v_bfe_u32 v5, v1, 16, 1
	v_bfe_u32 v24, v0, 16, 1
	v_bfe_u32 v26, v2, 16, 1
	v_add3_u32 v2, v2, v26, s9
	v_add3_u32 v3, v3, v25, s9
	v_add3_u32 v0, v0, v24, s9
	v_add3_u32 v1, v1, v5, s9
	v_perm_b32 v0, v1, v0, s10
	v_perm_b32 v1, v3, v2, s10
	global_store_dwordx2 v[20:21], v[0:1], off offset:1024
	s_nop 0
	v_pk_mul_f32 v[22:23], v[94:95], v[6:7] op_sel_hi:[1,0]
	v_pk_mul_f32 v[40:41], v[92:93], v[6:7] op_sel_hi:[1,0]
	s_waitcnt vmcnt(5)
	v_pk_mul_f32 v[2:3], v[22:23], v[126:127]
	v_pk_mul_f32 v[0:1], v[40:41], v[124:125]
	s_waitcnt vmcnt(4)
	v_pk_add_f32 v[22:23], v[130:131], 1.0 op_sel_hi:[1,0]
	v_pk_add_f32 v[24:25], v[128:129], 1.0 op_sel_hi:[1,0]
	s_waitcnt vmcnt(3)
	v_pk_fma_f32 v[2:3], v[2:3], v[22:23], v[134:135]
	v_pk_fma_f32 v[0:1], v[0:1], v[24:25], v[132:133]
	v_bfe_u32 v22, v3, 16, 1
	v_bfe_u32 v5, v1, 16, 1
	v_bfe_u32 v6, v0, 16, 1
	v_bfe_u32 v23, v2, 16, 1
	v_add3_u32 v2, v2, v23, s9
	v_add3_u32 v3, v3, v22, s9
	v_add3_u32 v0, v0, v6, s9
	v_add3_u32 v1, v1, v5, s9
	v_perm_b32 v0, v1, v0, s10
	v_perm_b32 v1, v3, v2, s10
	global_store_dwordx2 v[20:21], v[0:1], off offset:1536
	s_andn2_b64 exec, exec, s[6:7]
	s_cbranch_execz .LBB0_199
